# v39-spread-staging
# baseline (speedup 1.0000x reference)
.LBB0_655:
	s_waitcnt vmcnt(0)
	v_mov_b32_e32 v235, 0
	s_bitcmp1_b32 s72, 0
	s_cselect_b32 s46, 0x12800, 0
	s_xor_b32 s12, s46, 0x12800
	v_add_u32_e32 v230, s46, v181
	ds_read_b128 v[194:197], v230 offset:0
	ds_read_b128 v[198:201], v230 offset:32
	ds_read_b128 v[202:205], v230 offset:64
	ds_read_b128 v[206:209], v230 offset:96
	ds_read_b128 v[210:213], v230 offset:8704
	ds_read_b128 v[214:217], v230 offset:8736
	ds_read_b128 v[218:221], v230 offset:8768
	ds_read_b128 v[226:229], v230 offset:8800
	v_add_u32_e32 v231, s46, v185
	v_add_u32_e32 v232, 0x8800, v231
	v_add_u32_e32 v233, s12, v186
	v_add_u32_e32 v234, s12, v1
	s_branch .Ldf_qk

.Ldf_qk:
	s_waitcnt lgkmcnt(7)
	v_mfma_f32_32x32x16_bf16 v[82:97], v[194:197], v[158:161], v[2:17]
	s_waitcnt lgkmcnt(6)
	ds_read_b128 v[194:197], v230 offset:17408
	s_add_u32 s98, s44, s58
	s_addc_u32 s99, s45, 0
	v_lshl_add_u64 v[236:237], v[192:193], 0, s[98:99]
	global_load_dwordx4 v[162:165], v[236:237], off
	v_mfma_f32_32x32x16_bf16 v[82:97], v[198:201], v[154:157], v[82:97]
	s_waitcnt lgkmcnt(6)
	ds_read_b128 v[198:201], v230 offset:17440
	v_mfma_f32_32x32x16_bf16 v[82:97], v[202:205], v[150:153], v[82:97]
	s_waitcnt lgkmcnt(6)
	ds_read_b128 v[202:205], v230 offset:17472
	s_add_u32 s98, s44, s59
	s_addc_u32 s99, s45, 0
	v_lshl_add_u64 v[236:237], v[192:193], 0, s[98:99]
	global_load_dwordx4 v[166:169], v[236:237], off
	v_mfma_f32_32x32x16_bf16 v[82:97], v[206:209], v[146:149], v[82:97]
	s_waitcnt lgkmcnt(6)
	ds_read_b128 v[206:209], v230 offset:17504
	v_mfma_f32_32x32x16_bf16 v[98:113], v[210:213], v[158:161], v[2:17]
	s_waitcnt lgkmcnt(6)
	ds_read_b128 v[210:213], v230 offset:26112
	s_add_u32 s98, s44, s61
	s_addc_u32 s99, s45, 0
	v_lshl_add_u64 v[236:237], v[192:193], 0, s[98:99]
	global_load_dwordx4 v[170:173], v[236:237], off
	v_mfma_f32_32x32x16_bf16 v[98:113], v[214:217], v[154:157], v[98:113]
	s_waitcnt lgkmcnt(6)
	ds_read_b128 v[214:217], v230 offset:26144
	v_mfma_f32_32x32x16_bf16 v[98:113], v[218:221], v[150:153], v[98:113]
	s_waitcnt lgkmcnt(6)
	ds_read_b128 v[218:221], v230 offset:26176
	s_add_u32 s98, s44, s68
	s_addc_u32 s99, s45, 0
	v_lshl_add_u64 v[236:237], v[192:193], 0, s[98:99]
	global_load_dwordx4 v[174:177], v[236:237], off
	v_mfma_f32_32x32x16_bf16 v[98:113], v[226:229], v[146:149], v[98:113]
	s_waitcnt lgkmcnt(6)
	ds_read_b128 v[226:229], v230 offset:26208
	v_mfma_f32_32x32x16_bf16 v[114:129], v[194:197], v[158:161], v[2:17]
	s_waitcnt lgkmcnt(6)
	ds_read_b64_tr_b16 v[194:195], v231 offset:34816
	ds_read_b64_tr_b16 v[196:197], v231 offset:37376
	v_exp_f32_e32 v82, v82
	v_exp_f32_e32 v83, v83
	s_add_u32 s98, s44, s58
	s_addc_u32 s99, s45, 0
	v_lshl_add_u64 v[236:237], v[192:193], 0, s[98:99]
	global_load_dwordx4 v[238:241], v[236:237], off offset:2048
	v_add_f32_e32 v191, v191, v82
	v_add_f32_e32 v235, v235, v83
	v_cvt_pk_bf16_f32 v82, v82, v83
	v_mfma_f32_32x32x16_bf16 v[114:129], v[198:201], v[154:157], v[114:129]
	s_waitcnt lgkmcnt(7)
	ds_read_b64_tr_b16 v[198:199], v231 offset:34880
	ds_read_b64_tr_b16 v[200:201], v231 offset:37440
	v_exp_f32_e32 v84, v84
	v_exp_f32_e32 v85, v85
	v_add_f32_e32 v191, v191, v84
	v_add_f32_e32 v235, v235, v85
	v_cvt_pk_bf16_f32 v83, v84, v85
	v_mfma_f32_32x32x16_bf16 v[114:129], v[202:205], v[150:153], v[114:129]
	s_waitcnt lgkmcnt(8)
	ds_read_b64_tr_b16 v[202:203], v231 offset:34944
	ds_read_b64_tr_b16 v[204:205], v231 offset:37504
	v_exp_f32_e32 v86, v86
	v_exp_f32_e32 v87, v87
	s_add_u32 s98, s44, s59
	s_addc_u32 s99, s45, 0
	v_lshl_add_u64 v[236:237], v[192:193], 0, s[98:99]
	global_load_dwordx4 v[242:245], v[236:237], off offset:2048
	v_add_f32_e32 v191, v191, v86
	v_add_f32_e32 v235, v235, v87
	v_cvt_pk_bf16_f32 v84, v86, v87
	v_mfma_f32_32x32x16_bf16 v[114:129], v[206:209], v[146:149], v[114:129]
	s_waitcnt lgkmcnt(9)
	ds_read_b64_tr_b16 v[206:207], v231 offset:35008
	ds_read_b64_tr_b16 v[208:209], v231 offset:37568
	v_exp_f32_e32 v88, v88
	v_exp_f32_e32 v89, v89
	v_add_f32_e32 v191, v191, v88
	v_add_f32_e32 v235, v235, v89
	v_cvt_pk_bf16_f32 v85, v88, v89
	v_mfma_f32_32x32x16_bf16 v[130:145], v[210:213], v[158:161], v[2:17]
	s_waitcnt lgkmcnt(10)
	ds_read_b64_tr_b16 v[210:211], v231 offset:39936
	ds_read_b64_tr_b16 v[212:213], v231 offset:42496
	v_exp_f32_e32 v90, v90
	v_exp_f32_e32 v91, v91
	s_add_u32 s98, s44, s61
	s_addc_u32 s99, s45, 0
	v_lshl_add_u64 v[236:237], v[192:193], 0, s[98:99]
	global_load_dwordx4 v[246:249], v[236:237], off offset:2048
	v_add_f32_e32 v191, v191, v90
	v_add_f32_e32 v235, v235, v91
	v_cvt_pk_bf16_f32 v86, v90, v91
	v_mfma_f32_32x32x16_bf16 v[130:145], v[214:217], v[154:157], v[130:145]
	s_waitcnt lgkmcnt(11)
	ds_read_b64_tr_b16 v[214:215], v231 offset:40000
	ds_read_b64_tr_b16 v[216:217], v231 offset:42560
	v_exp_f32_e32 v92, v92
	v_exp_f32_e32 v93, v93
	v_add_f32_e32 v191, v191, v92
	v_add_f32_e32 v235, v235, v93
	v_cvt_pk_bf16_f32 v87, v92, v93
	v_mfma_f32_32x32x16_bf16 v[130:145], v[218:221], v[150:153], v[130:145]
	s_waitcnt lgkmcnt(12)
	ds_read_b64_tr_b16 v[218:219], v231 offset:40064
	ds_read_b64_tr_b16 v[220:221], v231 offset:42624
	v_exp_f32_e32 v94, v94
	v_exp_f32_e32 v95, v95
	s_add_u32 s98, s44, s68
	s_addc_u32 s99, s45, 0
	v_lshl_add_u64 v[236:237], v[192:193], 0, s[98:99]
	global_load_dwordx4 v[250:253], v[236:237], off offset:2048
	v_add_f32_e32 v191, v191, v94
	v_add_f32_e32 v235, v235, v95
	v_cvt_pk_bf16_f32 v88, v94, v95
	v_mfma_f32_32x32x16_bf16 v[130:145], v[226:229], v[146:149], v[130:145]
	s_waitcnt lgkmcnt(12)
	ds_read_b64_tr_b16 v[226:227], v231 offset:40128
	ds_read_b64_tr_b16 v[228:229], v231 offset:42688
	v_exp_f32_e32 v96, v96
	v_exp_f32_e32 v97, v97
	v_add_f32_e32 v191, v191, v96
	v_add_f32_e32 v235, v235, v97
	v_cvt_pk_bf16_f32 v89, v96, v97
	v_mfma_f32_32x32x16_bf16 v[50:65], v[194:197], v[82:85], v[50:65]
	s_waitcnt lgkmcnt(12)
	ds_read_b64_tr_b16 v[194:195], v231 offset:45056
	ds_read_b64_tr_b16 v[196:197], v231 offset:47616
	v_exp_f32_e32 v98, v98
	v_exp_f32_e32 v99, v99
	v_add_f32_e32 v191, v191, v98
	v_add_f32_e32 v235, v235, v99
	v_cvt_pk_bf16_f32 v98, v98, v99
	v_mfma_f32_32x32x16_bf16 v[66:81], v[198:201], v[82:85], v[66:81]
	s_waitcnt lgkmcnt(12)
	ds_read_b64_tr_b16 v[198:199], v231 offset:45120
	ds_read_b64_tr_b16 v[200:201], v231 offset:47680
	v_exp_f32_e32 v100, v100
	v_exp_f32_e32 v101, v101
	v_add_f32_e32 v191, v191, v100
	v_add_f32_e32 v235, v235, v101
	v_cvt_pk_bf16_f32 v99, v100, v101
	v_mfma_f32_32x32x16_bf16 v[34:49], v[202:205], v[82:85], v[34:49]
	s_waitcnt lgkmcnt(12)
	ds_read_b64_tr_b16 v[202:203], v231 offset:45184
	ds_read_b64_tr_b16 v[204:205], v231 offset:47744
	v_exp_f32_e32 v102, v102
	v_exp_f32_e32 v103, v103
	v_add_f32_e32 v191, v191, v102
	v_add_f32_e32 v235, v235, v103
	v_cvt_pk_bf16_f32 v100, v102, v103
	v_mfma_f32_32x32x16_bf16 v[18:33], v[206:209], v[82:85], v[18:33]
	s_waitcnt lgkmcnt(12)
	ds_read_b64_tr_b16 v[206:207], v231 offset:45248
	ds_read_b64_tr_b16 v[208:209], v231 offset:47808
	v_exp_f32_e32 v104, v104
	v_exp_f32_e32 v105, v105
	v_add_f32_e32 v191, v191, v104
	v_add_f32_e32 v235, v235, v105
	v_cvt_pk_bf16_f32 v101, v104, v105
	v_mfma_f32_32x32x16_bf16 v[50:65], v[210:213], v[86:89], v[50:65]
	s_waitcnt lgkmcnt(12)
	ds_read_b64_tr_b16 v[210:211], v231 offset:50176
	ds_read_b64_tr_b16 v[212:213], v231 offset:52736
	v_exp_f32_e32 v106, v106
	v_exp_f32_e32 v107, v107
	v_add_f32_e32 v191, v191, v106
	v_add_f32_e32 v235, v235, v107
	v_cvt_pk_bf16_f32 v102, v106, v107
	v_mfma_f32_32x32x16_bf16 v[66:81], v[214:217], v[86:89], v[66:81]
	s_waitcnt lgkmcnt(12)
	ds_read_b64_tr_b16 v[214:215], v231 offset:50240
	ds_read_b64_tr_b16 v[216:217], v231 offset:52800
	v_exp_f32_e32 v108, v108
	v_exp_f32_e32 v109, v109
	v_add_f32_e32 v191, v191, v108
	v_add_f32_e32 v235, v235, v109
	v_cvt_pk_bf16_f32 v103, v108, v109
	v_mfma_f32_32x32x16_bf16 v[34:49], v[218:221], v[86:89], v[34:49]
	s_waitcnt lgkmcnt(12)
	ds_read_b64_tr_b16 v[218:219], v231 offset:50304
	ds_read_b64_tr_b16 v[220:221], v231 offset:52864
	v_exp_f32_e32 v110, v110
	v_exp_f32_e32 v111, v111
	v_add_f32_e32 v191, v191, v110
	v_add_f32_e32 v235, v235, v111
	v_cvt_pk_bf16_f32 v104, v110, v111
	v_mfma_f32_32x32x16_bf16 v[18:33], v[226:229], v[86:89], v[18:33]
	s_waitcnt lgkmcnt(12)
	ds_read_b64_tr_b16 v[226:227], v231 offset:50368
	ds_read_b64_tr_b16 v[228:229], v231 offset:52928
	v_exp_f32_e32 v112, v112
	v_exp_f32_e32 v113, v113
	v_add_f32_e32 v191, v191, v112
	v_add_f32_e32 v235, v235, v113
	v_cvt_pk_bf16_f32 v105, v112, v113
	v_mfma_f32_32x32x16_bf16 v[50:65], v[194:197], v[98:101], v[50:65]
	s_waitcnt lgkmcnt(12)
	ds_read_b64_tr_b16 v[194:195], v232 offset:20480
	ds_read_b64_tr_b16 v[196:197], v232 offset:23040
	v_exp_f32_e32 v114, v114
	v_exp_f32_e32 v115, v115
	v_add_f32_e32 v191, v191, v114
	v_add_f32_e32 v235, v235, v115
	v_cvt_pk_bf16_f32 v114, v114, v115
	v_mfma_f32_32x32x16_bf16 v[66:81], v[198:201], v[98:101], v[66:81]
	s_waitcnt lgkmcnt(12)
	ds_read_b64_tr_b16 v[198:199], v232 offset:20544
	ds_read_b64_tr_b16 v[200:201], v232 offset:23104
	v_exp_f32_e32 v116, v116
	v_exp_f32_e32 v117, v117
	v_add_f32_e32 v191, v191, v116
	v_add_f32_e32 v235, v235, v117
	v_cvt_pk_bf16_f32 v115, v116, v117
	v_mfma_f32_32x32x16_bf16 v[34:49], v[202:205], v[98:101], v[34:49]
	s_waitcnt lgkmcnt(12)
	ds_read_b64_tr_b16 v[202:203], v232 offset:20608
	ds_read_b64_tr_b16 v[204:205], v232 offset:23168
	v_exp_f32_e32 v118, v118
	v_exp_f32_e32 v119, v119
	s_waitcnt vmcnt(7)
	ds_write_b128 v233, v[162:165] offset:0
	v_add_f32_e32 v191, v191, v118
	v_add_f32_e32 v235, v235, v119
	v_cvt_pk_bf16_f32 v116, v118, v119
	v_mfma_f32_32x32x16_bf16 v[18:33], v[206:209], v[98:101], v[18:33]
	s_waitcnt lgkmcnt(13)
	ds_read_b64_tr_b16 v[206:207], v232 offset:20672
	ds_read_b64_tr_b16 v[208:209], v232 offset:23232
	v_exp_f32_e32 v120, v120
	v_exp_f32_e32 v121, v121
	v_add_f32_e32 v191, v191, v120
	v_add_f32_e32 v235, v235, v121
	v_cvt_pk_bf16_f32 v117, v120, v121
	v_mfma_f32_32x32x16_bf16 v[50:65], v[210:213], v[102:105], v[50:65]
	s_waitcnt lgkmcnt(13)
	ds_read_b64_tr_b16 v[210:211], v232 offset:25600
	ds_read_b64_tr_b16 v[212:213], v232 offset:28160
	v_exp_f32_e32 v122, v122
	v_exp_f32_e32 v123, v123
	s_waitcnt vmcnt(6)
	s_waitcnt lgkmcnt(14)
	ds_write_b128 v233, v[166:169] offset:8704
	v_add_f32_e32 v191, v191, v122
	v_add_f32_e32 v235, v235, v123
	v_cvt_pk_bf16_f32 v118, v122, v123
	v_mfma_f32_32x32x16_bf16 v[66:81], v[214:217], v[102:105], v[66:81]
	s_waitcnt lgkmcnt(14)
	ds_read_b64_tr_b16 v[214:215], v232 offset:25664
	s_waitcnt lgkmcnt(14)
	ds_read_b64_tr_b16 v[216:217], v232 offset:28224
	v_exp_f32_e32 v124, v124
	v_exp_f32_e32 v125, v125
	v_add_f32_e32 v191, v191, v124
	v_add_f32_e32 v235, v235, v125
	v_cvt_pk_bf16_f32 v119, v124, v125
	v_mfma_f32_32x32x16_bf16 v[34:49], v[218:221], v[102:105], v[34:49]
	s_waitcnt lgkmcnt(14)
	ds_read_b64_tr_b16 v[218:219], v232 offset:25728
	s_waitcnt lgkmcnt(14)
	ds_read_b64_tr_b16 v[220:221], v232 offset:28288
	v_exp_f32_e32 v126, v126
	v_exp_f32_e32 v127, v127
	s_waitcnt vmcnt(5)
	s_waitcnt lgkmcnt(14)
	ds_write_b128 v233, v[170:173] offset:17408
	v_add_f32_e32 v191, v191, v126
	v_add_f32_e32 v235, v235, v127
	v_cvt_pk_bf16_f32 v120, v126, v127
	v_mfma_f32_32x32x16_bf16 v[18:33], v[226:229], v[102:105], v[18:33]
	s_waitcnt lgkmcnt(14)
	ds_read_b64_tr_b16 v[226:227], v232 offset:25792
	s_waitcnt lgkmcnt(14)
	ds_read_b64_tr_b16 v[228:229], v232 offset:28352
	v_exp_f32_e32 v128, v128
	v_exp_f32_e32 v129, v129
	v_add_f32_e32 v191, v191, v128
	v_add_f32_e32 v235, v235, v129
	v_cvt_pk_bf16_f32 v121, v128, v129
	v_mfma_f32_32x32x16_bf16 v[50:65], v[194:197], v[114:117], v[50:65]
	s_waitcnt lgkmcnt(14)
	ds_read_b64_tr_b16 v[194:195], v232 offset:30720
	s_waitcnt lgkmcnt(14)
	ds_read_b64_tr_b16 v[196:197], v232 offset:33280
	v_exp_f32_e32 v130, v130
	v_exp_f32_e32 v131, v131
	s_waitcnt vmcnt(4)
	s_waitcnt lgkmcnt(14)
	ds_write_b128 v233, v[174:177] offset:26112
	v_add_f32_e32 v191, v191, v130
	v_add_f32_e32 v235, v235, v131
	v_cvt_pk_bf16_f32 v130, v130, v131
	v_mfma_f32_32x32x16_bf16 v[66:81], v[198:201], v[114:117], v[66:81]
	s_waitcnt lgkmcnt(14)
	ds_read_b64_tr_b16 v[198:199], v232 offset:30784
	s_waitcnt lgkmcnt(14)
	ds_read_b64_tr_b16 v[200:201], v232 offset:33344
	v_exp_f32_e32 v132, v132
	v_exp_f32_e32 v133, v133
	v_add_f32_e32 v191, v191, v132
	v_add_f32_e32 v235, v235, v133
	v_cvt_pk_bf16_f32 v131, v132, v133
	v_mfma_f32_32x32x16_bf16 v[34:49], v[202:205], v[114:117], v[34:49]
	s_waitcnt lgkmcnt(14)
	ds_read_b64_tr_b16 v[202:203], v232 offset:30848
	s_waitcnt lgkmcnt(14)
	ds_read_b64_tr_b16 v[204:205], v232 offset:33408
	v_exp_f32_e32 v134, v134
	v_exp_f32_e32 v135, v135
	s_waitcnt vmcnt(3)
	s_waitcnt lgkmcnt(14)
	ds_write_b128 v234, v[238:241] offset:0
	v_add_f32_e32 v191, v191, v134
	v_add_f32_e32 v235, v235, v135
	v_cvt_pk_bf16_f32 v132, v134, v135
	v_mfma_f32_32x32x16_bf16 v[18:33], v[206:209], v[114:117], v[18:33]
	s_waitcnt lgkmcnt(14)
	ds_read_b64_tr_b16 v[206:207], v232 offset:30912
	s_waitcnt lgkmcnt(14)
	ds_read_b64_tr_b16 v[208:209], v232 offset:33472
	v_exp_f32_e32 v136, v136
	v_exp_f32_e32 v137, v137
	v_add_f32_e32 v191, v191, v136
	v_add_f32_e32 v235, v235, v137
	v_cvt_pk_bf16_f32 v133, v136, v137
	v_mfma_f32_32x32x16_bf16 v[50:65], v[210:213], v[118:121], v[50:65]
	s_waitcnt lgkmcnt(14)
	ds_read_b64_tr_b16 v[210:211], v232 offset:35840
	s_waitcnt lgkmcnt(14)
	ds_read_b64_tr_b16 v[212:213], v232 offset:38400
	v_exp_f32_e32 v138, v138
	v_exp_f32_e32 v139, v139
	s_waitcnt vmcnt(2)
	s_waitcnt lgkmcnt(14)
	ds_write_b128 v234, v[242:245] offset:10240
	v_add_f32_e32 v191, v191, v138
	v_add_f32_e32 v235, v235, v139
	v_cvt_pk_bf16_f32 v134, v138, v139
	v_mfma_f32_32x32x16_bf16 v[66:81], v[214:217], v[118:121], v[66:81]
	s_waitcnt lgkmcnt(14)
	ds_read_b64_tr_b16 v[214:215], v232 offset:35904
	s_waitcnt lgkmcnt(14)
	ds_read_b64_tr_b16 v[216:217], v232 offset:38464
	v_exp_f32_e32 v140, v140
	v_exp_f32_e32 v141, v141
	v_add_f32_e32 v191, v191, v140
	v_add_f32_e32 v235, v235, v141
	v_cvt_pk_bf16_f32 v135, v140, v141
	v_mfma_f32_32x32x16_bf16 v[34:49], v[218:221], v[118:121], v[34:49]
	s_waitcnt lgkmcnt(14)
	ds_read_b64_tr_b16 v[218:219], v232 offset:35968
	s_waitcnt lgkmcnt(14)
	ds_read_b64_tr_b16 v[220:221], v232 offset:38528
	v_exp_f32_e32 v142, v142
	v_exp_f32_e32 v143, v143
	s_waitcnt vmcnt(1)
	s_waitcnt lgkmcnt(14)
	ds_write_b128 v234, v[246:249] offset:20480
	v_add_f32_e32 v191, v191, v142
	v_add_f32_e32 v235, v235, v143
	v_cvt_pk_bf16_f32 v136, v142, v143
	v_mfma_f32_32x32x16_bf16 v[18:33], v[226:229], v[118:121], v[18:33]
	s_waitcnt lgkmcnt(14)
	ds_read_b64_tr_b16 v[226:227], v232 offset:36032
	s_waitcnt lgkmcnt(14)
	ds_read_b64_tr_b16 v[228:229], v232 offset:38592
	v_exp_f32_e32 v144, v144
	v_exp_f32_e32 v145, v145
	v_add_f32_e32 v191, v191, v144
	v_add_f32_e32 v235, v235, v145
	v_cvt_pk_bf16_f32 v137, v144, v145
	v_mfma_f32_32x32x16_bf16 v[50:65], v[194:197], v[130:133], v[50:65]
	s_waitcnt vmcnt(0)
	s_waitcnt lgkmcnt(14)
	ds_write_b128 v234, v[250:253] offset:30720
	v_mfma_f32_32x32x16_bf16 v[66:81], v[198:201], v[130:133], v[66:81]
	s_waitcnt lgkmcnt(14)
	v_mfma_f32_32x32x16_bf16 v[34:49], v[202:205], v[130:133], v[34:49]
	s_waitcnt lgkmcnt(11)
	v_mfma_f32_32x32x16_bf16 v[18:33], v[206:209], v[130:133], v[18:33]
	s_add_i32 s72, s72, 1
	s_add_u32 s44, s44, 0x180000
	s_addc_u32 s45, s45, 0
	s_cmp_eq_u32 s44, 0x2e80000
	s_waitcnt lgkmcnt(0)
	s_barrier
	s_cbranch_scc0 .Ldf_loop
	v_mfma_f32_32x32x16_bf16 v[50:65], v[210:213], v[134:137], v[50:65]
	v_mfma_f32_32x32x16_bf16 v[66:81], v[214:217], v[134:137], v[66:81]
	v_mfma_f32_32x32x16_bf16 v[34:49], v[218:221], v[134:137], v[34:49]
	v_mfma_f32_32x32x16_bf16 v[18:33], v[226:229], v[134:137], v[18:33]
	v_add_u32_e32 v238, 0x21480, v185
	v_add_u32_e32 v239, 0x21e80, v185
	v_add_u32_e32 v240, 0x214c0, v185
	v_add_u32_e32 v241, 0x21ec0, v185
	v_add_u32_e32 v242, 0x22800, v185
	v_add_u32_e32 v243, 0x23200, v185
	v_add_u32_e32 v244, 0x22840, v185
	v_add_u32_e32 v245, 0x23240, v185
	v_add_u32_e32 v246, 0x22880, v185
	v_add_u32_e32 v247, 0x23280, v185
	v_add_u32_e32 v248, 0x228c0, v185
	v_add_u32_e32 v249, 0x232c0, v185
	v_add_u32_e32 v250, 0x23c00, v185
	v_add_u32_e32 v251, 0x24600, v185
	v_add_u32_e32 v252, 0x23c40, v185
	v_add_u32_e32 v253, 0x24640, v185
	v_add_f32_e32 v191, v191, v235
	v_add_u32_e32 v82, 0x12800, v181
	ds_read_b128 v[82:85], v82
	v_add_u32_e32 v90, 0x12820, v181
	v_add_u32_e32 v94, 0x12840, v181
	v_add_u32_e32 v86, 0x14a00, v181
	ds_read_b128 v[86:89], v86
	v_add_u32_e32 v98, 0x12860, v181
	s_waitcnt lgkmcnt(1)
	v_mfma_f32_32x32x16_bf16 v[114:129], v[82:85], v[158:161], v[2:17]
	ds_read_b128 v[82:85], v90
	v_add_u32_e32 v90, 0x14a20, v181
	ds_read_b128 v[90:93], v90
	s_waitcnt lgkmcnt(1)
	v_mfma_f32_32x32x16_bf16 v[114:129], v[82:85], v[154:157], v[114:129]
	ds_read_b128 v[82:85], v94
	v_add_u32_e32 v94, 0x14a40, v181
	ds_read_b128 v[94:97], v94
	s_waitcnt lgkmcnt(1)
	v_mfma_f32_32x32x16_bf16 v[114:129], v[82:85], v[150:153], v[114:129]
	ds_read_b128 v[82:85], v98
	v_add_u32_e32 v98, 0x14a60, v181
	ds_read_b128 v[130:133], v98
	v_mfma_f32_32x32x16_bf16 v[98:113], v[86:89], v[158:161], v[2:17]
	v_add_u32_e32 v86, 0x18e00, v181
	ds_read_b128 v[168:171], v86
	v_mfma_f32_32x32x16_bf16 v[98:113], v[90:93], v[154:157], v[98:113]
	s_waitcnt lgkmcnt(3)
	v_mfma_f32_32x32x16_bf16 v[98:113], v[94:97], v[150:153], v[98:113]
	s_waitcnt lgkmcnt(2)
	v_mfma_f32_32x32x16_bf16 v[114:129], v[82:85], v[146:149], v[114:129]
	v_add_u32_e32 v82, 0x16c00, v181
	ds_read_b128 v[82:85], v82
	s_waitcnt lgkmcnt(2)
	v_mfma_f32_32x32x16_bf16 v[98:113], v[130:133], v[146:149], v[98:113]
	s_nop 7
	v_exp_f32_e32 v163, v114
	v_exp_f32_e32 v165, v116
	v_exp_f32_e32 v162, v117
	v_exp_f32_e32 v116, v119
	v_exp_f32_e32 v117, v120
	v_exp_f32_e32 v114, v122
	v_exp_f32_e32 v122, v124
	s_waitcnt lgkmcnt(0)
	v_mfma_f32_32x32x16_bf16 v[130:145], v[82:85], v[158:161], v[2:17]
	v_add_u32_e32 v82, 0x16c20, v181
	ds_read_b128 v[172:175], v82
	v_exp_f32_e32 v166, v98
	v_exp_f32_e32 v98, v121
	v_exp_f32_e32 v119, v126
	v_exp_f32_e32 v120, v127
	v_exp_f32_e32 v121, v128
	v_mfma_f32_32x32x16_bf16 v[82:97], v[168:171], v[158:161], v[2:17]
	v_exp_f32_e32 v168, v99
	v_add_u32_e32 v99, 0x18e20, v181
	ds_read_b128 v[192:195], v99
	v_add_u32_e32 v99, 0x16c40, v181
	v_exp_f32_e32 v124, v129
	ds_read_b128 v[126:129], v99
	v_add_u32_e32 v99, 0x18e40, v181
	s_waitcnt lgkmcnt(2)
	v_mfma_f32_32x32x16_bf16 v[130:145], v[172:175], v[154:157], v[130:145]
	ds_read_b128 v[174:177], v99
	v_add_u32_e32 v99, 0x16c60, v181
	v_exp_f32_e32 v169, v100
	v_exp_f32_e32 v173, v101
	v_exp_f32_e32 v160, v102
	v_exp_f32_e32 v159, v103
	ds_read_b128 v[100:103], v99
	s_waitcnt lgkmcnt(3)
	v_mfma_f32_32x32x16_bf16 v[82:97], v[192:195], v[154:157], v[82:97]
	v_add_u32_e32 v99, 0x18e60, v181
	ds_read_b128 v[196:199], v99
	v_exp_f32_e32 v164, v115
	v_exp_f32_e32 v118, v118
	v_exp_f32_e32 v158, v108
	v_exp_f32_e32 v167, v109
	v_exp_f32_e32 v161, v110
	s_waitcnt lgkmcnt(3)
	v_mfma_f32_32x32x16_bf16 v[130:145], v[126:129], v[150:153], v[130:145]
	v_exp_f32_e32 v126, v113
	v_exp_f32_e32 v129, v107
	v_exp_f32_e32 v115, v123
	v_exp_f32_e32 v123, v125
	v_exp_f32_e32 v170, v104
	v_exp_f32_e32 v171, v105
	v_exp_f32_e32 v172, v106
	s_waitcnt lgkmcnt(2)
	v_mfma_f32_32x32x16_bf16 v[82:97], v[174:177], v[150:153], v[82:97]
	v_exp_f32_e32 v127, v111
	v_exp_f32_e32 v128, v112
	s_waitcnt lgkmcnt(1)
	v_mfma_f32_32x32x16_bf16 v[130:145], v[100:103], v[146:149], v[130:145]
	s_waitcnt lgkmcnt(0)
	v_mfma_f32_32x32x16_bf16 v[82:97], v[196:199], v[146:149], v[82:97]
	s_nop 9
	v_exp_f32_e32 v99, v130
	v_exp_f32_e32 v100, v131
	v_exp_f32_e32 v113, v132
	v_exp_f32_e32 v101, v133
	v_exp_f32_e32 v102, v134
	v_exp_f32_e32 v103, v135
	v_add_u32_e32 v131, 0x1ba00, v185
	v_exp_f32_e32 v130, v82
	v_add_u32_e32 v82, 0x1b000, v185
	ds_read_b64_tr_b16 v[132:133], v82
	ds_read_b64_tr_b16 v[134:135], v131
	v_add_u32_e32 v82, 0x1b040, v185
	v_exp_f32_e32 v107, v140
	v_exp_f32_e32 v108, v141
	v_exp_f32_e32 v109, v142
	v_exp_f32_e32 v110, v143
	v_add_u32_e32 v131, 0x1ba40, v185
	ds_read_b64_tr_b16 v[140:141], v82
	ds_read_b64_tr_b16 v[142:143], v131
	v_exp_f32_e32 v156, v84
	v_add_u32_e32 v82, 0x1b080, v185
	v_add_u32_e32 v84, 0x1ba80, v185
	v_exp_f32_e32 v131, v83
	v_exp_f32_e32 v157, v85
	ds_read_b64_tr_b16 v[82:83], v82
	ds_read_b64_tr_b16 v[84:85], v84
	v_exp_f32_e32 v104, v136
	v_exp_f32_e32 v105, v137
	v_exp_f32_e32 v106, v138
	v_exp_f32_e32 v125, v139
	v_cvt_pk_bf16_f32 v136, v163, v164
	v_cvt_pk_bf16_f32 v137, v165, v162
	v_cvt_pk_bf16_f32 v138, v118, v116
	v_cvt_pk_bf16_f32 v139, v117, v98
	v_exp_f32_e32 v174, v86
	v_add_u32_e32 v86, 0x1b0c0, v185
	s_waitcnt lgkmcnt(4)
	v_mfma_f32_32x32x16_bf16 v[50:65], v[132:135], v[136:139], v[50:65]
	v_exp_f32_e32 v175, v87
	v_add_u32_e32 v87, 0x1bac0, v185
	ds_read_b64_tr_b16 v[132:133], v86
	ds_read_b64_tr_b16 v[134:135], v87
	v_exp_f32_e32 v176, v88
	v_exp_f32_e32 v177, v89
	v_cvt_pk_bf16_f32 v86, v114, v115
	v_cvt_pk_bf16_f32 v87, v122, v123
	s_waitcnt lgkmcnt(2)
	v_mfma_f32_32x32x16_bf16 v[34:49], v[82:85], v[136:139], v[34:49]
	v_add_u32_e32 v82, 0x1c400, v185
	v_add_u32_e32 v84, 0x1ce00, v185
	ds_read_b64_tr_b16 v[82:83], v82
	ds_read_b64_tr_b16 v[84:85], v84
	v_cvt_pk_bf16_f32 v88, v119, v120
	v_cvt_pk_bf16_f32 v89, v121, v124
	v_exp_f32_e32 v192, v90
	v_add_u32_e32 v90, 0x1c440, v185
	v_mfma_f32_32x32x16_bf16 v[66:81], v[140:143], v[136:139], v[66:81]
	v_exp_f32_e32 v193, v91
	v_exp_f32_e32 v91, v93
	v_exp_f32_e32 v93, v95
	v_add_u32_e32 v95, 0x1c4c0, v185
	v_exp_f32_e32 v111, v144
	v_add_u32_e32 v144, 0x1ec40, v185
	v_exp_f32_e32 v112, v145
	s_waitcnt lgkmcnt(2)
	v_mfma_f32_32x32x16_bf16 v[18:33], v[132:135], v[136:139], v[18:33]
	v_add_u32_e32 v134, 0x1ce40, v185
	ds_read_b64_tr_b16 v[132:133], v90
	ds_read_b64_tr_b16 v[134:135], v134
	v_exp_f32_e32 v90, v92
	v_exp_f32_e32 v92, v94
	v_exp_f32_e32 v94, v96
	v_add_u32_e32 v96, 0x1cec0, v185
	v_cvt_pk_bf16_f32 v136, v166, v168
	s_waitcnt lgkmcnt(2)
	v_mfma_f32_32x32x16_bf16 v[50:65], v[82:85], v[86:89], v[50:65]
	v_add_u32_e32 v82, 0x1c480, v185
	v_add_u32_e32 v84, 0x1ce80, v185
	ds_read_b64_tr_b16 v[82:83], v82
	ds_read_b64_tr_b16 v[84:85], v84
	v_cvt_pk_bf16_f32 v137, v169, v173
	v_cvt_pk_bf16_f32 v138, v160, v159
	v_cvt_pk_bf16_f32 v139, v170, v171
	s_waitcnt lgkmcnt(0)
	v_mfma_f32_32x32x16_bf16 v[34:49], v[82:85], v[86:89], v[34:49]
	v_add_u32_e32 v82, 0x1d800, v185
	v_add_u32_e32 v84, 0x1e200, v185
	v_mfma_f32_32x32x16_bf16 v[66:81], v[132:135], v[86:89], v[66:81]
	ds_read_b64_tr_b16 v[132:133], v95
	ds_read_b64_tr_b16 v[134:135], v96
	ds_read_b64_tr_b16 v[82:83], v82
	ds_read_b64_tr_b16 v[84:85], v84
	v_add_u32_e32 v96, 0x1d880, v185
	v_exp_f32_e32 v95, v97
	v_add_u32_e32 v97, 0x1d8c0, v185
	s_waitcnt lgkmcnt(2)
	v_mfma_f32_32x32x16_bf16 v[18:33], v[132:135], v[86:89], v[18:33]
	v_add_u32_e32 v86, 0x1d840, v185
	v_add_u32_e32 v88, 0x1e240, v185
	v_add_u32_e32 v134, 0x1e2c0, v185
	ds_read_b64_tr_b16 v[86:87], v86
	ds_read_b64_tr_b16 v[88:89], v88
	s_waitcnt lgkmcnt(2)
	v_mfma_f32_32x32x16_bf16 v[50:65], v[82:85], v[136:139], v[50:65]
	v_add_u32_e32 v84, 0x1e280, v185
	ds_read_b64_tr_b16 v[82:83], v96
	ds_read_b64_tr_b16 v[84:85], v84
	ds_read_b64_tr_b16 v[132:133], v97
	ds_read_b64_tr_b16 v[134:135], v134
	v_add_u32_e32 v96, 0x1ec00, v185
	v_add_u32_e32 v97, 0x1f600, v185
	ds_read_b64_tr_b16 v[140:141], v96
	ds_read_b64_tr_b16 v[142:143], v97
	ds_read_b64_tr_b16 v[144:145], v144
	v_add_f32_e32 v96, 0, v166
	v_add_f32_e32 v96, v168, v96
	v_add_f32_e32 v96, v169, v96
	v_add_f32_e32 v96, v173, v96
	s_waitcnt lgkmcnt(5)
	v_mfma_f32_32x32x16_bf16 v[34:49], v[82:85], v[136:139], v[34:49]
	v_add_u32_e32 v82, 0x1f640, v185
	v_add_f32_e32 v97, v160, v96
	ds_read_b64_tr_b16 v[146:147], v82
	v_add_u32_e32 v82, 0x1ec80, v185
	v_add_f32_e32 v97, v159, v97
	ds_read_b64_tr_b16 v[148:149], v82
	v_add_u32_e32 v82, 0x1f680, v185
	v_add_f32_e32 v97, v170, v97
	ds_read_b64_tr_b16 v[150:151], v82
	v_add_u32_e32 v82, 0x1ecc0, v185
	v_add_f32_e32 v97, v171, v97
	v_mfma_f32_32x32x16_bf16 v[66:81], v[86:89], v[136:139], v[66:81]
	v_cvt_pk_bf16_f32 v86, v172, v129
	v_cvt_pk_bf16_f32 v87, v158, v167
	v_cvt_pk_bf16_f32 v88, v161, v127
	v_cvt_pk_bf16_f32 v89, v128, v126
	ds_read_b64_tr_b16 v[152:153], v82
	v_add_u32_e32 v82, 0x1f6c0, v185
	v_add_f32_e32 v97, v172, v97
	ds_read_b64_tr_b16 v[154:155], v82
	s_waitcnt lgkmcnt(6)
	v_mfma_f32_32x32x16_bf16 v[50:65], v[140:143], v[86:89], v[50:65]
	v_add_u32_e32 v140, 0x20000, v185
	v_add_u32_e32 v142, 0x20a00, v185
	v_add_f32_e32 v97, v129, v97
	ds_read_b64_tr_b16 v[140:141], v140
	ds_read_b64_tr_b16 v[142:143], v142
	v_add_f32_e32 v97, v158, v97
	v_add_f32_e32 v97, v167, v97
	v_mfma_f32_32x32x16_bf16 v[18:33], v[132:135], v[136:139], v[18:33]
	v_add_f32_e32 v97, v161, v97
	v_add_f32_e32 v97, v127, v97
	v_add_f32_e32 v97, v128, v97
	v_add_f32_e32 v97, v126, v97
	v_cvt_pk_bf16_f32 v136, v130, v131
	v_add_u32_e32 v129, 0x200c0, v185
	v_add_f32_e32 v97, v130, v97
	v_add_f32_e32 v130, 0, v163
	s_waitcnt lgkmcnt(4)
	v_mfma_f32_32x32x16_bf16 v[34:49], v[148:151], v[86:89], v[34:49]
	ds_read_b64_tr_b16 v[148:149], v129
	v_add_u32_e32 v129, 0x20ac0, v185
	v_add_u32_e32 v126, 0x21400, v185
	v_add_u32_e32 v128, 0x21e00, v185
	v_add_f32_e32 v130, v164, v130
	v_cvt_pk_bf16_f32 v82, v99, v100
	v_cvt_pk_bf16_f32 v83, v113, v101
	v_cvt_pk_bf16_f32 v84, v102, v103
	v_cvt_pk_bf16_f32 v85, v104, v105
	v_mfma_f32_32x32x16_bf16 v[66:81], v[144:147], v[86:89], v[66:81]
	ds_read_b64_tr_b16 v[150:151], v129
	ds_read_b64_tr_b16 v[126:127], v126
	ds_read_b64_tr_b16 v[128:129], v128
	v_add_f32_e32 v130, v165, v130
	v_add_f32_e32 v130, v162, v130
	v_add_f32_e32 v118, v118, v130
	v_add_f32_e32 v116, v116, v118
	s_waitcnt lgkmcnt(6)
	v_mfma_f32_32x32x16_bf16 v[18:33], v[152:155], v[86:89], v[18:33]
	v_add_u32_e32 v86, 0x20080, v185
	v_add_u32_e32 v88, 0x20a80, v185
	ds_read_b64_tr_b16 v[86:87], v86
	ds_read_b64_tr_b16 v[88:89], v88
	v_add_u32_e32 v144, 0x20040, v185
	v_add_u32_e32 v146, 0x20a40, v185
	v_add_f32_e32 v116, v117, v116
	s_waitcnt lgkmcnt(6)
	v_mfma_f32_32x32x16_bf16 v[50:65], v[140:143], v[82:85], v[50:65]
	ds_read_b64_tr_b16 v[144:145], v144
	ds_read_b64_tr_b16 v[146:147], v146
	v_add_f32_e32 v98, v98, v116
	v_add_f32_e32 v98, v114, v98
	v_add_f32_e32 v98, v115, v98
	v_cvt_pk_bf16_f32 v132, v106, v125
	v_cvt_pk_bf16_f32 v133, v107, v108
	v_cvt_pk_bf16_f32 v134, v109, v110
	v_cvt_pk_bf16_f32 v135, v111, v112
	v_add_f32_e32 v98, v122, v98
	v_add_f32_e32 v98, v123, v98
	s_waitcnt lgkmcnt(4)
	v_mfma_f32_32x32x16_bf16 v[50:65], v[126:129], v[132:135], v[50:65]
	v_add_f32_e32 v98, v119, v98
	v_add_f32_e32 v98, v120, v98
	v_add_f32_e32 v97, v131, v97
	v_add_f32_e32 v98, v121, v98
	v_add_u32_e32 v140, 0x21440, v185
	v_add_u32_e32 v142, 0x21e40, v185
	v_add_f32_e32 v97, v156, v97
	s_waitcnt lgkmcnt(2)
	v_mfma_f32_32x32x16_bf16 v[34:49], v[86:89], v[82:85], v[34:49]
	v_add_f32_e32 v98, v124, v98
	v_cvt_pk_bf16_f32 v137, v156, v157
	ds_read_b64_tr_b16 v[140:141], v140
	ds_read_b64_tr_b16 v[142:143], v142
	v_add_f32_e32 v97, v157, v97
	v_add_f32_e32 v98, v99, v98
	v_add_f32_e32 v98, v100, v98
	s_waitcnt lgkmcnt(2)
	v_mfma_f32_32x32x16_bf16 v[66:81], v[144:147], v[82:85], v[66:81]
	ds_read_b64_tr_b16 v[144:145], v238
	ds_read_b64_tr_b16 v[146:147], v239
	ds_read_b64_tr_b16 v[152:153], v240
	ds_read_b64_tr_b16 v[154:155], v241
	ds_read_b64_tr_b16 v[86:87], v242
	ds_read_b64_tr_b16 v[88:89], v243
	ds_read_b64_tr_b16 v[156:157], v244
	ds_read_b64_tr_b16 v[158:159], v245
	v_cvt_pk_bf16_f32 v138, v174, v175
	v_cvt_pk_bf16_f32 v139, v176, v177
	v_add_f32_e32 v98, v113, v98
	v_add_f32_e32 v97, v174, v97
	v_add_f32_e32 v97, v175, v97
	s_waitcnt lgkmcnt(2)
	v_mfma_f32_32x32x16_bf16 v[50:65], v[86:89], v[136:139], v[50:65]
	v_add_f32_e32 v86, v101, v98
	v_add_f32_e32 v86, v102, v86
	v_add_f32_e32 v86, v103, v86
	v_add_f32_e32 v97, v176, v97
	v_add_f32_e32 v86, v104, v86
	v_add_f32_e32 v97, v177, v97
	v_add_f32_e32 v86, v105, v86
	v_mfma_f32_32x32x16_bf16 v[34:49], v[144:147], v[132:135], v[34:49]
	v_add_f32_e32 v97, v192, v97
	v_add_f32_e32 v86, v106, v86
	v_add_f32_e32 v97, v193, v97
	v_add_f32_e32 v86, v125, v86
	v_add_f32_e32 v97, v90, v97
	v_add_f32_e32 v86, v107, v86
	v_add_f32_e32 v97, v91, v97
	v_mfma_f32_32x32x16_bf16 v[18:33], v[148:151], v[82:85], v[18:33]
	ds_read_b64_tr_b16 v[82:83], v246
	ds_read_b64_tr_b16 v[84:85], v247
	ds_read_b64_tr_b16 v[148:149], v248
	ds_read_b64_tr_b16 v[150:151], v249
	v_add_f32_e32 v86, v108, v86
	v_add_f32_e32 v97, v92, v97
	v_add_f32_e32 v86, v109, v86
	ds_read_b64_tr_b16 v[126:127], v250
	ds_read_b64_tr_b16 v[128:129], v251
	ds_read_b64_tr_b16 v[164:165], v252
	ds_read_b64_tr_b16 v[166:167], v253
	v_add_f32_e32 v97, v93, v97
	v_add_f32_e32 v86, v110, v86
	s_waitcnt lgkmcnt(6)
	v_mfma_f32_32x32x16_bf16 v[34:49], v[82:85], v[136:139], v[34:49]
	v_mov_b32_e32 v83, v179
	v_add_f32_e32 v97, v94, v97
	v_add_f32_e32 v86, v111, v86
	v_add_f32_e32 v97, v95, v97
	v_add_f32_e32 v86, v112, v86
	v_add_f32_e32 v86, v86, v97
	v_add_f32_e32 v82, v191, v86
	v_mfma_f32_32x32x16_bf16 v[66:81], v[140:143], v[132:135], v[66:81]
	ds_read_b64_tr_b16 v[140:141], v254
	ds_read_b64_tr_b16 v[142:143], v187
	ds_read_b64_tr_b16 v[160:161], v222
	ds_read_b64_tr_b16 v[162:163], v223
	s_waitcnt lgkmcnt(0)
	s_barrier
	v_cvt_pk_bf16_f32 v96, v192, v193
	v_mbcnt_lo_u32_b32 v83, -1, v83
	v_mfma_f32_32x32x16_bf16 v[18:33], v[152:155], v[132:135], v[18:33]
	v_mbcnt_hi_u32_b32 v87, -1, v83
	v_lshlrev_b32_e32 v83, 2, v87
	v_xor_b32_e32 v85, 0x80, v83
	ds_bpermute_b32 v83, v85, v82
	v_cvt_pk_bf16_f32 v97, v90, v91
	v_cvt_pk_bf16_f32 v98, v92, v93
	v_cvt_pk_bf16_f32 v99, v94, v95
	v_mfma_f32_32x32x16_bf16 v[66:81], v[156:159], v[136:139], v[66:81]
	s_waitcnt lgkmcnt(0)
	v_add_f32_e32 v82, v82, v83
	v_div_scale_f32 v83, s[44:45], v82, v82, 1.0
	v_rcp_f32_e32 v84, v83
	s_nop 0
	v_fma_f32 v86, -v83, v84, 1.0
	v_mfma_f32_32x32x16_bf16 v[18:33], v[148:151], v[136:139], v[18:33]
	v_fmac_f32_e32 v84, v86, v84
	v_div_scale_f32 v86, vcc, 1.0, v82, 1.0
	v_mul_f32_e32 v88, v86, v84
	v_fma_f32 v89, -v83, v88, v86
	v_fmac_f32_e32 v88, v89, v84
	v_fma_f32 v83, -v83, v88, v86
	v_mfma_f32_32x32x16_bf16 v[50:65], v[126:129], v[96:99], v[50:65]
	v_div_fmas_f32 v83, v83, v84, v88
	v_and_b32_e32 v86, 31, v87
	v_ashrrev_i32_e32 v87, 5, v87
	v_div_fixup_f32 v83, v83, v82, 1.0
	v_lshlrev_b32_e32 v82, 9, v87
	v_lshlrev_b32_e32 v88, 2, v86
	v_mul_f32_e32 v84, v224, v83
	v_mfma_f32_32x32x16_bf16 v[66:81], v[164:167], v[96:99], v[66:81]
	s_and_b64 vcc, exec, s[6:7]
	v_add3_u32 v82, s28, v82, v88
	v_mfma_f32_32x32x16_bf16 v[34:49], v[140:143], v[96:99], v[34:49]
	v_mfma_f32_32x32x16_bf16 v[18:33], v[160:163], v[96:99], v[18:33]
	s_cbranch_vccnz .LBB0_658
	v_mul_f32_e32 v88, v50, v84
	v_mul_f32_e32 v89, v51, v84
	ds_write2_b32 v82, v88, v89 offset1:32
	v_mul_f32_e32 v88, v52, v84
	v_mul_f32_e32 v89, v53, v84
	ds_write2_b32 v82, v88, v89 offset0:64 offset1:96
	v_mul_f32_e32 v88, v54, v84
	v_mul_f32_e32 v89, v55, v84
	v_add_u32_e32 v90, 0x400, v82
	ds_write2_b32 v90, v88, v89 offset1:32
	v_mul_f32_e32 v88, v56, v84
	v_mul_f32_e32 v89, v57, v84
	ds_write2_b32 v90, v88, v89 offset0:64 offset1:96
	v_mul_f32_e32 v88, v58, v84
	v_mul_f32_e32 v89, v59, v84
	v_add_u32_e32 v90, 0x800, v82
	ds_write2_b32 v90, v88, v89 offset1:32
	v_mul_f32_e32 v88, v60, v84
	v_mul_f32_e32 v89, v61, v84
	ds_write2_b32 v90, v88, v89 offset0:64 offset1:96
	v_mul_f32_e32 v88, v62, v84
	v_mul_f32_e32 v89, v63, v84
	v_add_u32_e32 v90, 0xc00, v82
	ds_write2_b32 v90, v88, v89 offset1:32
	v_mul_f32_e32 v88, v64, v84
	v_mul_f32_e32 v89, v65, v84
	ds_write2_b32 v90, v88, v89 offset0:64 offset1:96
	v_mul_f32_e32 v88, v66, v84
	v_mul_f32_e32 v89, v67, v84
	v_add_u32_e32 v90, 0x1000, v82
	ds_write2_b32 v90, v88, v89 offset1:32
	v_mul_f32_e32 v88, v68, v84
	v_mul_f32_e32 v89, v69, v84
	ds_write2_b32 v90, v88, v89 offset0:64 offset1:96
	v_mul_f32_e32 v88, v70, v84
	v_mul_f32_e32 v89, v71, v84
	v_add_u32_e32 v90, 0x1400, v82
	ds_write2_b32 v90, v88, v89 offset1:32
	v_mul_f32_e32 v88, v72, v84
	v_mul_f32_e32 v89, v73, v84
	ds_write2_b32 v90, v88, v89 offset0:64 offset1:96
	v_mul_f32_e32 v88, v74, v84
	v_mul_f32_e32 v89, v75, v84
	v_add_u32_e32 v90, 0x1800, v82
	ds_write2_b32 v90, v88, v89 offset1:32
	v_mul_f32_e32 v88, v76, v84
	v_mul_f32_e32 v89, v77, v84
	ds_write2_b32 v90, v88, v89 offset0:64 offset1:96
	v_mul_f32_e32 v88, v78, v84
	v_mul_f32_e32 v89, v79, v84
	v_add_u32_e32 v90, 0x1c00, v82
	ds_write2_b32 v90, v88, v89 offset1:32
	v_mul_f32_e32 v88, v80, v84
	v_mul_f32_e32 v89, v81, v84
	ds_write2_b32 v90, v88, v89 offset0:64 offset1:96
	v_mul_f32_e32 v88, v34, v84
	v_mul_f32_e32 v89, v35, v84
	v_add_u32_e32 v90, 0x2000, v82
	ds_write2_b32 v90, v88, v89 offset1:32
	v_mul_f32_e32 v88, v36, v84
	v_mul_f32_e32 v89, v37, v84
	ds_write2_b32 v90, v88, v89 offset0:64 offset1:96
	v_mul_f32_e32 v88, v38, v84
	v_mul_f32_e32 v89, v39, v84
	v_add_u32_e32 v90, 0x2400, v82
	ds_write2_b32 v90, v88, v89 offset1:32
	v_mul_f32_e32 v88, v40, v84
	v_mul_f32_e32 v89, v41, v84
	ds_write2_b32 v90, v88, v89 offset0:64 offset1:96
	v_mul_f32_e32 v88, v42, v84
	v_mul_f32_e32 v89, v43, v84
	v_add_u32_e32 v90, 0x2800, v82
	ds_write2_b32 v90, v88, v89 offset1:32
	v_mul_f32_e32 v88, v44, v84
	v_mul_f32_e32 v89, v45, v84
	ds_write2_b32 v90, v88, v89 offset0:64 offset1:96
	v_mul_f32_e32 v88, v46, v84
	v_mul_f32_e32 v89, v47, v84
	v_add_u32_e32 v90, 0x2c00, v82
	ds_write2_b32 v90, v88, v89 offset1:32
	v_mul_f32_e32 v88, v48, v84
	v_mul_f32_e32 v89, v49, v84
	ds_write2_b32 v90, v88, v89 offset0:64 offset1:96
	v_mul_f32_e32 v88, v18, v84
	v_mul_f32_e32 v89, v19, v84
	v_add_u32_e32 v90, 0x3000, v82
	ds_write2_b32 v90, v88, v89 offset1:32
	v_mul_f32_e32 v88, v20, v84
	v_mul_f32_e32 v89, v21, v84
	ds_write2_b32 v90, v88, v89 offset0:64 offset1:96
	v_mul_f32_e32 v88, v22, v84
	v_mul_f32_e32 v89, v23, v84
	v_add_u32_e32 v90, 0x3400, v82
	ds_write2_b32 v90, v88, v89 offset1:32
	v_mul_f32_e32 v88, v24, v84
	v_mul_f32_e32 v89, v25, v84
	ds_write2_b32 v90, v88, v89 offset0:64 offset1:96
	v_mul_f32_e32 v88, v26, v84
	v_mul_f32_e32 v89, v27, v84
	v_add_u32_e32 v90, 0x3800, v82
	ds_write2_b32 v90, v88, v89 offset1:32
	v_mul_f32_e32 v88, v28, v84
	v_mul_f32_e32 v89, v29, v84
	ds_write2_b32 v90, v88, v89 offset0:64 offset1:96
	v_mul_f32_e32 v88, v30, v84
	v_mul_f32_e32 v89, v31, v84
	v_add_u32_e32 v90, 0x3c00, v82
	ds_write2_b32 v90, v88, v89 offset1:32
	v_mul_f32_e32 v88, v32, v84
	v_mul_f32_e32 v89, v33, v84
	ds_write2_b32 v90, v88, v89 offset0:64 offset1:96

	.amdhsa_kernel _Z10hybrid_fwd4Args
		.amdhsa_group_segment_fixed_size 0
		.amdhsa_private_segment_fixed_size 0
		.amdhsa_kernarg_size 528
		.amdhsa_user_sgpr_count 2
		.amdhsa_user_sgpr_dispatch_ptr 0
		.amdhsa_user_sgpr_queue_ptr 0
		.amdhsa_user_sgpr_kernarg_segment_ptr 1
		.amdhsa_user_sgpr_dispatch_id 0
		.amdhsa_user_sgpr_kernarg_preload_length 0
		.amdhsa_user_sgpr_kernarg_preload_offset 0
		.amdhsa_user_sgpr_private_segment_size 0
		.amdhsa_uses_dynamic_stack 0
		.amdhsa_enable_private_segment 0
		.amdhsa_system_sgpr_workgroup_id_x 1
		.amdhsa_system_sgpr_workgroup_id_y 0
		.amdhsa_system_sgpr_workgroup_id_z 0
		.amdhsa_system_sgpr_workgroup_info 0
		.amdhsa_system_vgpr_workitem_id 2
		.amdhsa_next_free_vgpr 256
		.amdhsa_next_free_sgpr 102
		.amdhsa_accum_offset 256
		.amdhsa_reserve_vcc 1
		.amdhsa_float_round_mode_32 0
		.amdhsa_float_round_mode_16_64 0
		.amdhsa_float_denorm_mode_32 3
		.amdhsa_float_denorm_mode_16_64 3
		.amdhsa_dx10_clamp 1
		.amdhsa_ieee_mode 1
		.amdhsa_fp16_overflow 0
		.amdhsa_tg_split 0
		.amdhsa_exception_fp_ieee_invalid_op 0
		.amdhsa_exception_fp_denorm_src 0
		.amdhsa_exception_fp_ieee_div_zero 0
		.amdhsa_exception_fp_ieee_overflow 0
		.amdhsa_exception_fp_ieee_underflow 0
		.amdhsa_exception_fp_ieee_inexact 0
		.amdhsa_exception_int_div_zero 0
	.end_amdhsa_kernel

amdhsa.kernels:
  - .agpr_count:     0
    .args:
      - .offset:         0
        .size:           272
        .value_kind:     by_value
      - .offset:         272
        .size:           4
        .value_kind:     hidden_block_count_x
      - .offset:         276
        .size:           4
        .value_kind:     hidden_block_count_y
      - .offset:         280
        .size:           4
        .value_kind:     hidden_block_count_z
      - .offset:         284
        .size:           2
        .value_kind:     hidden_group_size_x
      - .offset:         286
        .size:           2
        .value_kind:     hidden_group_size_y
      - .offset:         288
        .size:           2
        .value_kind:     hidden_group_size_z
      - .offset:         290
        .size:           2
        .value_kind:     hidden_remainder_x
      - .offset:         292
        .size:           2
        .value_kind:     hidden_remainder_y
      - .offset:         294
        .size:           2
        .value_kind:     hidden_remainder_z
      - .offset:         312
        .size:           8
        .value_kind:     hidden_global_offset_x
      - .offset:         320
        .size:           8
        .value_kind:     hidden_global_offset_y
      - .offset:         328
        .size:           8
        .value_kind:     hidden_global_offset_z
      - .offset:         336
        .size:           2
        .value_kind:     hidden_grid_dims
      - .offset:         360
        .size:           8
        .value_kind:     hidden_multigrid_sync_arg
      - .offset:         392
        .size:           4
        .value_kind:     hidden_dynamic_lds_size
    .group_segment_fixed_size: 0
    .kernarg_segment_align: 8
    .kernarg_segment_size: 528
    .language:       OpenCL C
    .language_version:
      - 2
      - 0
    .max_flat_workgroup_size: 512
    .name:           _Z10hybrid_fwd4Args
    .private_segment_fixed_size: 0
    .sgpr_count:     108
    .sgpr_spill_count: 15
    .symbol:         _Z10hybrid_fwd4Args.kd
    .uniform_work_group_size: 1
    .uses_dynamic_stack: false
    .vgpr_count:     256
    .vgpr_spill_count: 0
    .wavefront_size: 64
